# attn loop v3: raw-P preserved, sum-triggered rescale, C-init block instead of per-tile movs
# speedup vs baseline: 1.0010x; 1.0010x over previous
; #define A_LOAD(t) do { kreg0 = *(const u32x4*)(kg + (size_t)((t) * 64 + kv0) * 768 + kc0 * 8); if (tid < 256) kreg1 = *(const u32x4*)(kg + (size_t)((t) * 64 + kv1) * 768 + kc1 * 8); \
;         vreg = *(const u32x4*)(vg + (size_t)(t) * 64 * 512); } while (0)
; __device__ __forceinline__ void attn_unit(LAS unsigned char* lds, const bf16* Q, const bf16* Kp, const bf16* V, bf16* Y, int b, int h, int qb) {
;     ...
;     const int kv0 = tid / 12, kc0 = tid % 12, kv1 = (tid + 512) / 12, kc1 = (tid + 512) % 12;
;     const bf16* kg = Kp + rowbase * 768 + h * 96;
;     const bf16* vg = V + (rowbase + (tid & 63)) * 512 + h * 64 + 8 * (tid >> 6);
;     u32x4 kreg0, kreg1 = (u32x4){0, 0, 0, 0}, vreg;
;     ...
;     A_LOAD(0); A_STORE(0);
;     __syncthreads();
;     float m_run = 0.f, l_run = 0.f;
;     f32x16 o[2];
; #pragma unroll
;     for (int i = 0; i < 16; ++i) { o[0][i] = 0.f; o[1][i] = 0.f; }
;     const int qrel = wid * 32 + r32;
.LBB0_3632:
	s_or_b64 exec, exec, s[10:11]
	v_and_b32_e32 v11, 63, v4
	v_or_b32_e32 v4, s13, v11
	v_lshlrev_b32_e32 v4, 10, v4
	v_mov_b32_e32 v5, v64
	v_lshl_add_u64 v[4:5], s[64:65], 0, v[4:5]
	s_lshl_b32 s80, s9, 7
	v_lshl_add_u64 v[14:15], v[4:5], 0, s[80:81]
	v_lshlrev_b32_e32 v4, 3, v8
	v_ashrrev_i32_e32 v5, 31, v4
	v_lshl_add_u64 v[14:15], v[4:5], 1, v[14:15]
	flat_load_dwordx4 v[100:103], v[14:15]
	s_movk_i32 s10, 0xd0
	v_mul_lo_u32 v65, v9, s10
	v_lshlrev_b32_e32 v111, 4, v12
	v_add3_u32 v12, 0, v65, v111
	v_lshlrev_b32_e32 v113, 4, v13
	s_waitcnt vmcnt(0) lgkmcnt(0)
	ds_write_b128 v12, v[92:95]
	s_and_saveexec_b64 s[10:11], vcc
	s_xor_b64 s[10:11], exec, s[10:11]
	v_lshlrev_b32_e32 v113, 4, v13
	s_or_saveexec_b64 s[10:11], s[10:11]
	s_movk_i32 s13, 0xd0
	v_mul_lo_u32 v114, v10, s13
	s_xor_b64 exec, exec, s[10:11]
	v_add3_u32 v12, 0, v114, v113
	ds_write_b128 v12, v[96:99]
	s_or_b64 exec, exec, s[10:11]
	v_lshl_add_u64 v[66:67], v[0:1], 1, s[6:7]
	v_lshl_add_u64 v[106:107], v[2:3], 1, s[6:7]
	s_movk_i32 s6, 0xd0
	v_lshlrev_b32_e32 v12, 3, v6
	v_mad_u32_u24 v0, v7, s6, 0
	v_mul_i32_i24_e32 v1, 0xffffffb8, v7
	v_lshl_add_u32 v117, v6, 4, v0
	v_add3_u32 v118, v0, v1, v12
	v_mov_b32_e32 v0, s80
	v_mov_b32_e32 v1, v64
	v_lshlrev_b32_e32 v2, 10, v11
	s_movk_i32 s10, 0x440
	v_lshl_add_u64 v[0:1], v[4:5], 1, v[0:1]
	v_lshl_or_b32 v2, s23, 23, v2
	v_mov_b32_e32 v3, v64
	s_lshl_b32 s12, s12, 2
	v_mul_lo_u32 v8, v8, s10
	v_lshlrev_b32_e32 v13, 1, v11
	v_lshlrev_b32_e32 v112, 2, v6
	s_lshl_b32 s15, s22, 8
	v_lshl_add_u64 v[0:1], v[0:1], 0, v[2:3]
	v_mov_b32_e32 v123, 0
	s_lshl_b32 s9, s9, 6
	s_add_i32 s12, s12, 4
	s_mov_b32 s13, 1
	v_add3_u32 v115, 0, v8, v13
	v_or_b32_e32 v116, s14, v7
	s_or_b32 s14, s14, 31
	v_or_b32_e32 v119, s15, v112
	s_lshl_b32 s22, s22, 2
	v_add_u32_e32 v120, 64, v10
	v_add_u32_e32 v121, 64, v9
	v_lshl_add_u64 v[108:109], s[4:5], 0, v[0:1]
	s_mov_b32 s23, 0
	v_mov_b32_e32 v122, 0
	v_mov_b32_e32 v16, 0
	v_mov_b32_e32 v17, v123
	v_mov_b32_e32 v18, v123
	v_mov_b32_e32 v19, v123
	v_mov_b32_e32 v20, v123
	v_mov_b32_e32 v21, v123
	v_mov_b32_e32 v22, v123
	v_mov_b32_e32 v23, v123
	v_mov_b32_e32 v24, v123
	v_mov_b32_e32 v25, v123
	v_mov_b32_e32 v26, v123
	v_mov_b32_e32 v27, v123
	v_mov_b32_e32 v28, v123
	v_mov_b32_e32 v29, v123
	v_mov_b32_e32 v30, v123
	v_mov_b32_e32 v31, v123
	v_mov_b32_e32 v0, v123
	v_mov_b32_e32 v1, v123
	v_mov_b32_e32 v2, v123
	v_mov_b32_e32 v3, v123
	v_mov_b32_e32 v4, v123
	v_mov_b32_e32 v5, v123
	v_mov_b32_e32 v6, v123
	v_mov_b32_e32 v7, v123
	v_mov_b32_e32 v8, v123
	v_mov_b32_e32 v9, v123
	v_mov_b32_e32 v10, v123
	v_mov_b32_e32 v11, v123
	v_mov_b32_e32 v12, v123
	v_mov_b32_e32 v13, v123
	v_mov_b32_e32 v14, v123
	v_mov_b32_e32 v15, v123
	ds_write_b16 v115, v100 offset:26624
	ds_write_b16_d16_hi v115, v100 offset:26760
	ds_write_b16 v115, v101 offset:26896
	ds_write_b16_d16_hi v115, v101 offset:27032
	ds_write_b16 v115, v102 offset:27168
	ds_write_b16_d16_hi v115, v102 offset:27304
	ds_write_b16 v115, v103 offset:27440
	ds_write_b16_d16_hi v115, v103 offset:27576
	v_mov_b32_e32 v142, 0
	v_mov_b32_e32 v143, 0
	v_mov_b32_e32 v144, 0
	v_mov_b32_e32 v145, 0
	v_mov_b32_e32 v146, 0
	v_mov_b32_e32 v147, 0
	v_mov_b32_e32 v148, 0
	v_mov_b32_e32 v149, 0
	v_mov_b32_e32 v150, 0
	v_mov_b32_e32 v151, 0
	v_mov_b32_e32 v152, 0
	v_mov_b32_e32 v153, 0
	v_mov_b32_e32 v154, 0
	v_mov_b32_e32 v155, 0
	v_mov_b32_e32 v156, 0
	v_mov_b32_e32 v157, 0
	s_mov_b64 s[66:67], -1
	s_waitcnt lgkmcnt(0)
	s_barrier
	s_branch .Lat_head

; #define LAS __attribute__((address_space(3)))
; #define A_LOAD(t) do { kreg0 = *(const u32x4*)(kg + (size_t)((t) * 64 + kv0) * 768 + kc0 * 8); if (tid < 256) kreg1 = *(const u32x4*)(kg + (size_t)((t) * 64 + kv1) * 768 + kc1 * 8); \
;         vreg = *(const u32x4*)(vg + (size_t)(t) * 64 * 512); } while (0)
; __device__ __forceinline__ void attn_unit(LAS unsigned char* lds, const bf16* Q, const bf16* Kp, const bf16* V, bf16* Y, int b, int h, int qb) {
;     ...
;     for (int t = 0; t < NT; ++t) {
;         const int buf = t & 1;
;         if (t + 1 < NT) A_LOAD(t + 1);
;         const int jb = t - (NT - 4);
;         const bool skip = (jb >= 0) && (64 * jb > wid * 32 + 31);
;         if (!skip) {
;             f32x16 p0, p1;
;             const float nm = -m_run;
; #pragma unroll
;             for (int i = 0; i < 16; ++i) { p0[i] = nm; p1[i] = nm; }
;             LAS const unsigned char* kb = lds + KOFF + buf * KBUF + r32 * KPB + hi * 16;
;             LAS const unsigned char* vb = lds + VOFF + buf * VBUF + r32 * VPB + hi * 8;
; #pragma unroll
;             for (int d0 = 0; d0 < 6; ++d0) p0 = __builtin_amdgcn_mfma_f32_32x32x16_bf16(*(LAS const bf16x8*)(kb + 32 * d0), qr[d0], p0, 0, 0, 0);
; #pragma unroll
;             for (int d0 = 0; d0 < 6; ++d0) p1 = __builtin_amdgcn_mfma_f32_32x32x16_bf16(*(LAS const bf16x8*)(kb + 32 * KPB + 32 * d0), qr[d0], p1, 0, 0, 0);
.Lat_noload:
	s_add_i32 s10, s13, -1
	s_and_b32 s24, s10, 1
	s_add_i32 s10, s22, s13
	s_addk_i32 s10, 0xff83
	s_cmp_gt_i32 s10, -1
	s_cselect_b64 s[10:11], -1, 0
	s_add_i32 s25, s15, s23
	s_addk_i32 s25, 0xe100
	s_cmp_gt_i32 s25, s14
	s_cselect_b64 s[26:27], -1, 0
	s_and_b64 s[26:27], s[10:11], s[26:27]
	s_and_b64 vcc, exec, s[26:27]
	s_cbranch_vccnz .Lat_stage
	s_mul_i32 s25, s24, 0x3400
	v_add_u32_e32 v110, s25, v117
	s_mul_i32 s25, s24, 0x2200
	v_add_u32_e32 v125, s25, v118
	ds_read_b128 v[172:175], v110
	ds_read_b128 v[176:179], v110 offset:32
	ds_read_b128 v[180:183], v110 offset:64
	ds_read_b128 v[184:187], v110 offset:96
	ds_read_b128 v[188:191], v110 offset:128
	ds_read_b128 v[192:195], v110 offset:160
	ds_read_b128 v[198:201], v110 offset:6656
	ds_read_b128 v[202:205], v110 offset:6688
	ds_read_b128 v[206:209], v110 offset:6720
	ds_read_b128 v[222:225], v110 offset:6752
	ds_read_b128 v[226:229], v110 offset:6784
	ds_read_b128 v[230:233], v110 offset:6816
	v_add_u32_e32 v124, 0x6800, v125
	v_add_u32_e32 v125, 0x7800, v125
	s_waitcnt lgkmcnt(11)
	v_mfma_f32_32x32x16_bf16 v[32:47], v[172:175], v[68:71], v[142:157]
	ds_read2_b64 v[234:237], v124 offset1:2
	s_waitcnt lgkmcnt(11)
	v_mfma_f32_32x32x16_bf16 v[32:47], v[176:179], v[72:75], v[32:47]
	ds_read2_b64 v[238:241], v124 offset0:4 offset1:6
	s_waitcnt lgkmcnt(11)
	v_mfma_f32_32x32x16_bf16 v[32:47], v[180:183], v[76:79], v[32:47]
	ds_read2_b64 v[242:245], v125 offset0:32 offset1:34
	s_waitcnt lgkmcnt(11)
	v_mfma_f32_32x32x16_bf16 v[32:47], v[184:187], v[80:83], v[32:47]
	ds_read2_b64 v[246:249], v125 offset0:36 offset1:38
	s_waitcnt lgkmcnt(11)
	v_mfma_f32_32x32x16_bf16 v[32:47], v[188:191], v[84:87], v[32:47]
	s_waitcnt lgkmcnt(10)
	v_mfma_f32_32x32x16_bf16 v[32:47], v[192:195], v[88:91], v[32:47]
	s_waitcnt lgkmcnt(9)
	v_mfma_f32_32x32x16_bf16 v[48:63], v[198:201], v[68:71], v[142:157]
	s_waitcnt lgkmcnt(8)
	v_mfma_f32_32x32x16_bf16 v[48:63], v[202:205], v[72:75], v[48:63]
	s_waitcnt lgkmcnt(7)
	v_mfma_f32_32x32x16_bf16 v[48:63], v[206:209], v[76:79], v[48:63]
	s_nop 5
	s_andn2_b64 vcc, exec, s[10:11]
	s_cbranch_vccnz .Lat_nomask0
	v_add_u32_e32 v126, s23, v119
	v_sub_u32_e32 v126, v116, v126
	v_add_u32_e32 v126, 0x1f00, v126
	v_cmp_gt_i32_e32 vcc, 0, v126
	v_cmp_gt_i32_e64 s[40:41], 1, v126
	v_cmp_gt_i32_e64 s[42:43], 2, v126
	v_cndmask_b32_e32 v32, v32, v221, vcc
	v_cmp_gt_i32_e32 vcc, 3, v126
	v_cndmask_b32_e64 v33, v33, v221, s[40:41]
	v_cmp_gt_i32_e64 s[40:41], 8, v126
	v_cndmask_b32_e64 v34, v34, v221, s[42:43]
	v_cmp_gt_i32_e64 s[42:43], 9, v126
	v_cndmask_b32_e32 v35, v35, v221, vcc
	v_cmp_gt_i32_e32 vcc, 10, v126
	v_cndmask_b32_e64 v36, v36, v221, s[40:41]
	v_cmp_gt_i32_e64 s[40:41], 11, v126
	v_cndmask_b32_e64 v37, v37, v221, s[42:43]
	v_cmp_gt_i32_e64 s[42:43], 16, v126
	v_cndmask_b32_e32 v38, v38, v221, vcc
	v_cmp_gt_i32_e32 vcc, 17, v126
	v_cndmask_b32_e64 v39, v39, v221, s[40:41]
	v_cmp_gt_i32_e64 s[40:41], 18, v126
	v_cndmask_b32_e64 v40, v40, v221, s[42:43]
	v_cmp_gt_i32_e64 s[42:43], 19, v126
	v_cndmask_b32_e32 v41, v41, v221, vcc
	v_cmp_gt_i32_e32 vcc, 24, v126
	v_cndmask_b32_e64 v42, v42, v221, s[40:41]
	v_cmp_gt_i32_e64 s[40:41], 25, v126
	v_cndmask_b32_e64 v43, v43, v221, s[42:43]
	v_cmp_gt_i32_e64 s[42:43], 26, v126
	v_cndmask_b32_e32 v44, v44, v221, vcc
	v_cmp_gt_i32_e32 vcc, 27, v126
	v_cndmask_b32_e64 v45, v45, v221, s[40:41]
	v_cndmask_b32_e64 v46, v46, v221, s[42:43]
	s_nop 0
	v_cndmask_b32_e32 v47, v47, v221, vcc
; __device__ __forceinline__ void attn_unit(LAS unsigned char* lds, const bf16* Q, const bf16* Kp, const bf16* V, bf16* Y, int b, int h, int qb) {
;     ...
;             ATT_HALF(p0, 0, 0);
;             ATT_HALF(p1, 32, 2);
.Lat_nomask0:
	v_exp_f32_e32 v172, v32
	v_exp_f32_e32 v173, v33
	v_exp_f32_e32 v174, v34
	v_exp_f32_e32 v175, v35
	s_waitcnt lgkmcnt(6)
	v_mfma_f32_32x32x16_bf16 v[48:63], v[222:225], v[80:83], v[48:63]
	v_exp_f32_e32 v176, v36
	v_exp_f32_e32 v177, v37
	v_exp_f32_e32 v178, v38
	v_exp_f32_e32 v179, v39
	s_waitcnt lgkmcnt(5)
	v_mfma_f32_32x32x16_bf16 v[48:63], v[226:229], v[84:87], v[48:63]
	v_exp_f32_e32 v180, v40
	v_exp_f32_e32 v181, v41
	v_exp_f32_e32 v182, v42
	v_exp_f32_e32 v183, v43
	s_waitcnt lgkmcnt(4)
	v_mfma_f32_32x32x16_bf16 v[48:63], v[230:233], v[88:91], v[48:63]
	v_exp_f32_e32 v184, v44
	v_exp_f32_e32 v185, v45
	v_exp_f32_e32 v186, v46
	v_exp_f32_e32 v187, v47
	ds_read2_b64 v[198:201], v124 offset0:8 offset1:10
	ds_read2_b64 v[202:205], v124 offset0:12 offset1:14
	ds_read2_b64 v[206:209], v125 offset0:40 offset1:42
	ds_read2_b64 v[222:225], v125 offset0:44 offset1:46
	v_add_f32_e32 v138, v172, v174
	v_add_f32_e32 v139, v173, v175
	v_cvt_pk_bf16_f32 v130, v172, v173
	v_cvt_pk_bf16_f32 v131, v174, v175
	v_add_f32_e32 v138, v138, v176
	v_add_f32_e32 v139, v139, v177
	v_cvt_pk_bf16_f32 v132, v176, v177
	v_add_f32_e32 v138, v138, v178
	v_add_f32_e32 v139, v139, v179
	v_cvt_pk_bf16_f32 v133, v178, v179
	v_add_f32_e32 v138, v138, v180
	v_add_f32_e32 v139, v139, v181
	v_cvt_pk_bf16_f32 v134, v180, v181
	v_add_f32_e32 v138, v138, v182
	v_add_f32_e32 v139, v139, v183
	v_cvt_pk_bf16_f32 v135, v182, v183
	v_add_f32_e32 v138, v138, v184
	v_add_f32_e32 v139, v139, v185
	v_cvt_pk_bf16_f32 v136, v184, v185
	v_add_f32_e32 v138, v138, v186
	v_add_f32_e32 v139, v139, v187
	v_cvt_pk_bf16_f32 v137, v186, v187
	v_add_f32_e32 v138, v138, v139
	v_cmp_lt_f32_e32 vcc, 0x43800000, v138
	s_or_b64 vcc, vcc, s[66:67]
	s_cbranch_vccnz .Lat_slow0
.Lat_cont0:
	v_add_f32_e32 v123, v123, v138
	s_waitcnt lgkmcnt(4)
	v_mfma_f32_32x32x16_bf16 v[16:31], v[234:237], v[130:133], v[16:31]
	s_andn2_b64 vcc, exec, s[10:11]
	s_cbranch_vccnz .Lat_nomask1
	v_add_u32_e32 v126, s23, v119
	v_sub_u32_e32 v126, v116, v126
	v_add_u32_e32 v126, 0x1f00, v126
	v_cmp_gt_i32_e32 vcc, 32, v126
	v_cmp_gt_i32_e64 s[40:41], 33, v126
	v_cmp_gt_i32_e64 s[42:43], 34, v126
	v_cndmask_b32_e32 v48, v48, v221, vcc
	v_cmp_gt_i32_e32 vcc, 35, v126
	v_cndmask_b32_e64 v49, v49, v221, s[40:41]
	v_cmp_gt_i32_e64 s[40:41], 40, v126
	v_cndmask_b32_e64 v50, v50, v221, s[42:43]
	v_cmp_gt_i32_e64 s[42:43], 41, v126
	v_cndmask_b32_e32 v51, v51, v221, vcc
	v_cmp_gt_i32_e32 vcc, 42, v126
	v_cndmask_b32_e64 v52, v52, v221, s[40:41]
	v_cmp_gt_i32_e64 s[40:41], 43, v126
	v_cndmask_b32_e64 v53, v53, v221, s[42:43]
	v_cmp_gt_i32_e64 s[42:43], 48, v126
	v_cndmask_b32_e32 v54, v54, v221, vcc
	v_cmp_gt_i32_e32 vcc, 49, v126
	v_cndmask_b32_e64 v55, v55, v221, s[40:41]
	v_cmp_gt_i32_e64 s[40:41], 50, v126
	v_cndmask_b32_e64 v56, v56, v221, s[42:43]
	v_cmp_gt_i32_e64 s[42:43], 51, v126
	v_cndmask_b32_e32 v57, v57, v221, vcc
	v_cmp_gt_i32_e32 vcc, 56, v126
	v_cndmask_b32_e64 v58, v58, v221, s[40:41]
	v_cmp_gt_i32_e64 s[40:41], 57, v126
	v_cndmask_b32_e64 v59, v59, v221, s[42:43]
	v_cmp_gt_i32_e64 s[42:43], 58, v126
	v_cndmask_b32_e32 v60, v60, v221, vcc
	v_cmp_gt_i32_e32 vcc, 59, v126
	v_cndmask_b32_e64 v61, v61, v221, s[40:41]
	v_cndmask_b32_e64 v62, v62, v221, s[42:43]
	s_nop 0
	v_cndmask_b32_e32 v63, v63, v221, vcc
.Lat_nomask1:
	v_exp_f32_e32 v188, v48
	v_exp_f32_e32 v189, v49
	v_mfma_f32_32x32x16_bf16 v[0:15], v[242:245], v[130:133], v[0:15]
	v_exp_f32_e32 v190, v50
	v_exp_f32_e32 v191, v51
	v_exp_f32_e32 v192, v52
	v_exp_f32_e32 v193, v53
	v_exp_f32_e32 v194, v54
	v_exp_f32_e32 v195, v55
	v_mfma_f32_32x32x16_bf16 v[16:31], v[238:241], v[134:137], v[16:31]
	v_exp_f32_e32 v216, v56
	v_exp_f32_e32 v217, v57
	v_exp_f32_e32 v218, v58
	v_exp_f32_e32 v219, v59
	v_exp_f32_e32 v250, v60
	v_exp_f32_e32 v251, v61
	v_mfma_f32_32x32x16_bf16 v[0:15], v[246:249], v[134:137], v[0:15]
	v_exp_f32_e32 v140, v62
	v_exp_f32_e32 v141, v63
	v_add_f32_e32 v138, v188, v190
	v_add_f32_e32 v139, v189, v191
	v_cvt_pk_bf16_f32 v130, v188, v189
	v_cvt_pk_bf16_f32 v131, v190, v191
	v_add_f32_e32 v138, v138, v192
	v_add_f32_e32 v139, v139, v193
	v_cvt_pk_bf16_f32 v132, v192, v193
	v_add_f32_e32 v138, v138, v194
	v_add_f32_e32 v139, v139, v195
	v_cvt_pk_bf16_f32 v133, v194, v195
	v_add_f32_e32 v138, v138, v216
	v_add_f32_e32 v139, v139, v217
	v_cvt_pk_bf16_f32 v134, v216, v217
	v_add_f32_e32 v138, v138, v218
	v_add_f32_e32 v139, v139, v219
	v_cvt_pk_bf16_f32 v135, v218, v219
	v_add_f32_e32 v138, v138, v250
	v_add_f32_e32 v139, v139, v251
	v_cvt_pk_bf16_f32 v136, v250, v251
	v_add_f32_e32 v138, v138, v140
	v_add_f32_e32 v139, v139, v141
	v_cvt_pk_bf16_f32 v137, v140, v141
	v_add_f32_e32 v138, v138, v139
	v_cmp_lt_f32_e32 vcc, 0x43800000, v138
	s_cbranch_vccnz .Lat_slow1
.Lat_cont1:
	v_add_f32_e32 v123, v123, v138
	s_waitcnt lgkmcnt(0)
	v_mfma_f32_32x32x16_bf16 v[16:31], v[198:201], v[130:133], v[16:31]
	v_mfma_f32_32x32x16_bf16 v[0:15], v[206:209], v[130:133], v[0:15]
	v_mfma_f32_32x32x16_bf16 v[16:31], v[202:205], v[134:137], v[16:31]
	v_mfma_f32_32x32x16_bf16 v[0:15], v[222:225], v[134:137], v[0:15]

; __device__ __forceinline__ void attn_unit(LAS unsigned char* lds, const bf16* Q, const bf16* Kp, const bf16* V, bf16* Y, int b, int h, int qb) {
;     ...
;         __syncthreads();
.Lat_latch:
	s_add_i32 s13, s13, 1
	s_add_i32 s23, s23, 64
	s_add_i32 s6, s22, s13
	s_cmpk_lg_i32 s6, 0x81
	s_mov_b64 s[6:7], 0x10000
	v_lshl_add_u64 v[108:109], v[108:109], 0, s[6:7]
	s_waitcnt lgkmcnt(0)
	s_barrier
	s_cbranch_scc1 .Lat_head
	s_branch .LBB0_3656
.Lat_slow0:
	s_nop 7
	v_max3_f32 v127, v32, v33, v34
	v_max3_f32 v128, v35, v36, v37
	v_max3_f32 v127, v127, v38, v39
	v_max3_f32 v128, v128, v40, v41
	v_max3_f32 v127, v127, v42, v43
	v_max3_f32 v128, v128, v44, v45
	v_max3_f32 v127, v127, v46, v47
	v_max_f32_e32 v127, v127, v128
	v_mov_b32_e32 v128, v127
	s_nop 1
	v_permlane32_swap_b32_e32 v127, v128
	v_max_f32_e32 v127, v127, v128
	v_max_f32_e32 v128, 0, v127
	s_nop 0
	v_cndmask_b32_e64 v128, v128, v127, s[66:67]
	s_mov_b64 s[66:67], 0
	v_exp_f32_e64 v129, -v128
	v_add_f32_e32 v122, v122, v128
	v_sub_f32_e32 v32, v32, v128
	v_sub_f32_e32 v33, v33, v128
	v_sub_f32_e32 v34, v34, v128
	v_sub_f32_e32 v35, v35, v128
	v_sub_f32_e32 v36, v36, v128
	v_sub_f32_e32 v37, v37, v128
	v_sub_f32_e32 v38, v38, v128
	v_sub_f32_e32 v39, v39, v128
	v_sub_f32_e32 v40, v40, v128
	v_sub_f32_e32 v41, v41, v128
	v_sub_f32_e32 v42, v42, v128
	v_sub_f32_e32 v43, v43, v128
	v_sub_f32_e32 v44, v44, v128
	v_sub_f32_e32 v45, v45, v128
	v_sub_f32_e32 v46, v46, v128
	v_sub_f32_e32 v47, v47, v128
	v_sub_f32_e32 v48, v48, v128
	v_sub_f32_e32 v49, v49, v128
	v_sub_f32_e32 v50, v50, v128
	v_sub_f32_e32 v51, v51, v128
	v_sub_f32_e32 v52, v52, v128
	v_sub_f32_e32 v53, v53, v128
	v_sub_f32_e32 v54, v54, v128
	v_sub_f32_e32 v55, v55, v128
	v_sub_f32_e32 v56, v56, v128
	v_sub_f32_e32 v57, v57, v128
	v_sub_f32_e32 v58, v58, v128
	v_sub_f32_e32 v59, v59, v128
	v_sub_f32_e32 v60, v60, v128
	v_sub_f32_e32 v61, v61, v128
	v_sub_f32_e32 v62, v62, v128
	v_sub_f32_e32 v63, v63, v128
	v_sub_f32_e32 v142, v142, v128
	v_sub_f32_e32 v143, v143, v128
	v_sub_f32_e32 v144, v144, v128
	v_sub_f32_e32 v145, v145, v128
	v_sub_f32_e32 v146, v146, v128
	v_sub_f32_e32 v147, v147, v128
	v_sub_f32_e32 v148, v148, v128
	v_sub_f32_e32 v149, v149, v128
	v_sub_f32_e32 v150, v150, v128
	v_sub_f32_e32 v151, v151, v128
	v_sub_f32_e32 v152, v152, v128
	v_sub_f32_e32 v153, v153, v128
	v_sub_f32_e32 v154, v154, v128
	v_sub_f32_e32 v155, v155, v128
	v_sub_f32_e32 v156, v156, v128
	v_sub_f32_e32 v157, v157, v128
	v_mul_f32_e32 v0, v0, v129
	v_mul_f32_e32 v1, v1, v129
	v_mul_f32_e32 v2, v2, v129
	v_mul_f32_e32 v3, v3, v129
	v_mul_f32_e32 v4, v4, v129
	v_mul_f32_e32 v5, v5, v129
	v_mul_f32_e32 v6, v6, v129
	v_mul_f32_e32 v7, v7, v129
	v_mul_f32_e32 v8, v8, v129
	v_mul_f32_e32 v9, v9, v129
	v_mul_f32_e32 v10, v10, v129
	v_mul_f32_e32 v11, v11, v129
	v_mul_f32_e32 v12, v12, v129
	v_mul_f32_e32 v13, v13, v129
	v_mul_f32_e32 v14, v14, v129
	v_mul_f32_e32 v15, v15, v129
	v_mul_f32_e32 v16, v16, v129
	v_mul_f32_e32 v17, v17, v129
	v_mul_f32_e32 v18, v18, v129
	v_mul_f32_e32 v19, v19, v129
	v_mul_f32_e32 v20, v20, v129
	v_mul_f32_e32 v21, v21, v129
	v_mul_f32_e32 v22, v22, v129
	v_mul_f32_e32 v23, v23, v129
	v_mul_f32_e32 v24, v24, v129
	v_mul_f32_e32 v25, v25, v129
	v_mul_f32_e32 v26, v26, v129
	v_mul_f32_e32 v27, v27, v129
	v_mul_f32_e32 v28, v28, v129
	v_mul_f32_e32 v29, v29, v129
	v_mul_f32_e32 v30, v30, v129
	v_mul_f32_e32 v31, v31, v129
	v_mul_f32_e32 v123, v123, v129
	v_exp_f32_e32 v172, v32
	v_exp_f32_e32 v173, v33
	v_exp_f32_e32 v174, v34
	v_exp_f32_e32 v175, v35
	v_exp_f32_e32 v176, v36
	v_exp_f32_e32 v177, v37
	v_exp_f32_e32 v178, v38
	v_exp_f32_e32 v179, v39
	v_exp_f32_e32 v180, v40
	v_exp_f32_e32 v181, v41
	v_exp_f32_e32 v182, v42
	v_exp_f32_e32 v183, v43
	v_exp_f32_e32 v184, v44
	v_exp_f32_e32 v185, v45
	v_exp_f32_e32 v186, v46
	v_exp_f32_e32 v187, v47
	v_add_f32_e32 v138, v172, v174
	v_add_f32_e32 v139, v173, v175
	v_cvt_pk_bf16_f32 v130, v172, v173
	v_cvt_pk_bf16_f32 v131, v174, v175
	v_add_f32_e32 v138, v138, v176
	v_add_f32_e32 v139, v139, v177
	v_cvt_pk_bf16_f32 v132, v176, v177
	v_add_f32_e32 v138, v138, v178
	v_add_f32_e32 v139, v139, v179
	v_cvt_pk_bf16_f32 v133, v178, v179
	v_add_f32_e32 v138, v138, v180
	v_add_f32_e32 v139, v139, v181
	v_cvt_pk_bf16_f32 v134, v180, v181
	v_add_f32_e32 v138, v138, v182
	v_add_f32_e32 v139, v139, v183
	v_cvt_pk_bf16_f32 v135, v182, v183
	v_add_f32_e32 v138, v138, v184
	v_add_f32_e32 v139, v139, v185
	v_cvt_pk_bf16_f32 v136, v184, v185
	v_add_f32_e32 v138, v138, v186
	v_add_f32_e32 v139, v139, v187
	v_cvt_pk_bf16_f32 v137, v186, v187
	v_add_f32_e32 v138, v138, v139
	s_branch .Lat_cont0
.Lat_slow1:
	s_nop 7
	v_max3_f32 v127, v48, v49, v50
	v_max3_f32 v128, v51, v52, v53
	v_max3_f32 v127, v127, v54, v55
	v_max3_f32 v128, v128, v56, v57
	v_max3_f32 v127, v127, v58, v59
	v_max3_f32 v128, v128, v60, v61
	v_max3_f32 v127, v127, v62, v63
	v_max_f32_e32 v127, v127, v128
	v_mov_b32_e32 v128, v127
	s_nop 1
	v_permlane32_swap_b32_e32 v127, v128
	v_max_f32_e32 v127, v127, v128
	v_max_f32_e32 v128, 0, v127
	v_exp_f32_e64 v129, -v128
	v_add_f32_e32 v122, v122, v128
	v_sub_f32_e32 v48, v48, v128
	v_sub_f32_e32 v49, v49, v128
	v_sub_f32_e32 v50, v50, v128
	v_sub_f32_e32 v51, v51, v128
	v_sub_f32_e32 v52, v52, v128
	v_sub_f32_e32 v53, v53, v128
	v_sub_f32_e32 v54, v54, v128
	v_sub_f32_e32 v55, v55, v128
	v_sub_f32_e32 v56, v56, v128
	v_sub_f32_e32 v57, v57, v128
	v_sub_f32_e32 v58, v58, v128
	v_sub_f32_e32 v59, v59, v128
	v_sub_f32_e32 v60, v60, v128
	v_sub_f32_e32 v61, v61, v128
	v_sub_f32_e32 v62, v62, v128
	v_sub_f32_e32 v63, v63, v128
	v_sub_f32_e32 v142, v142, v128
	v_sub_f32_e32 v143, v143, v128
	v_sub_f32_e32 v144, v144, v128
	v_sub_f32_e32 v145, v145, v128
	v_sub_f32_e32 v146, v146, v128
	v_sub_f32_e32 v147, v147, v128
	v_sub_f32_e32 v148, v148, v128
	v_sub_f32_e32 v149, v149, v128
	v_sub_f32_e32 v150, v150, v128
	v_sub_f32_e32 v151, v151, v128
	v_sub_f32_e32 v152, v152, v128
	v_sub_f32_e32 v153, v153, v128
	v_sub_f32_e32 v154, v154, v128
	v_sub_f32_e32 v155, v155, v128
	v_sub_f32_e32 v156, v156, v128
	v_sub_f32_e32 v157, v157, v128
	v_mul_f32_e32 v0, v0, v129
	v_mul_f32_e32 v1, v1, v129
	v_mul_f32_e32 v2, v2, v129
	v_mul_f32_e32 v3, v3, v129
	v_mul_f32_e32 v4, v4, v129
	v_mul_f32_e32 v5, v5, v129
	v_mul_f32_e32 v6, v6, v129
	v_mul_f32_e32 v7, v7, v129
	v_mul_f32_e32 v8, v8, v129
	v_mul_f32_e32 v9, v9, v129
	v_mul_f32_e32 v10, v10, v129
	v_mul_f32_e32 v11, v11, v129
	v_mul_f32_e32 v12, v12, v129
	v_mul_f32_e32 v13, v13, v129
	v_mul_f32_e32 v14, v14, v129
	v_mul_f32_e32 v15, v15, v129
	v_mul_f32_e32 v16, v16, v129
	v_mul_f32_e32 v17, v17, v129
	v_mul_f32_e32 v18, v18, v129
	v_mul_f32_e32 v19, v19, v129
	v_mul_f32_e32 v20, v20, v129
	v_mul_f32_e32 v21, v21, v129
	v_mul_f32_e32 v22, v22, v129
	v_mul_f32_e32 v23, v23, v129
	v_mul_f32_e32 v24, v24, v129
	v_mul_f32_e32 v25, v25, v129
	v_mul_f32_e32 v26, v26, v129
	v_mul_f32_e32 v27, v27, v129
	v_mul_f32_e32 v28, v28, v129
	v_mul_f32_e32 v29, v29, v129
	v_mul_f32_e32 v30, v30, v129
	v_mul_f32_e32 v31, v31, v129
	v_mul_f32_e32 v123, v123, v129
	v_exp_f32_e32 v188, v48
	v_exp_f32_e32 v189, v49
	v_exp_f32_e32 v190, v50
	v_exp_f32_e32 v191, v51
	v_exp_f32_e32 v192, v52
	v_exp_f32_e32 v193, v53
	v_exp_f32_e32 v194, v54
	v_exp_f32_e32 v195, v55
	v_exp_f32_e32 v216, v56
	v_exp_f32_e32 v217, v57
	v_exp_f32_e32 v218, v58
	v_exp_f32_e32 v219, v59
	v_exp_f32_e32 v250, v60
	v_exp_f32_e32 v251, v61
	v_exp_f32_e32 v140, v62
	v_exp_f32_e32 v141, v63
	v_add_f32_e32 v138, v188, v190
	v_add_f32_e32 v139, v189, v191
	v_cvt_pk_bf16_f32 v130, v188, v189
	v_cvt_pk_bf16_f32 v131, v190, v191
	v_add_f32_e32 v138, v138, v192
	v_add_f32_e32 v139, v139, v193
	v_cvt_pk_bf16_f32 v132, v192, v193
	v_add_f32_e32 v138, v138, v194
	v_add_f32_e32 v139, v139, v195
	v_cvt_pk_bf16_f32 v133, v194, v195
	v_add_f32_e32 v138, v138, v216
	v_add_f32_e32 v139, v139, v217
	v_cvt_pk_bf16_f32 v134, v216, v217
	v_add_f32_e32 v138, v138, v218
	v_add_f32_e32 v139, v139, v219
	v_cvt_pk_bf16_f32 v135, v218, v219
	v_add_f32_e32 v138, v138, v250
	v_add_f32_e32 v139, v139, v251
	v_cvt_pk_bf16_f32 v136, v250, v251
	v_add_f32_e32 v138, v138, v140
	v_add_f32_e32 v139, v139, v141
	v_cvt_pk_bf16_f32 v137, v140, v141
	v_add_f32_e32 v138, v138, v139
	s_branch .Lat_cont1
